# P3 stage 3: cross-row sums via v_permlane16/32_swap instead of 32 ds_bpermute round trips (on top of the P3 prefetch)
# baseline (speedup 1.0000x reference)
; #define LAS __attribute__((address_space(3)))
; #define MFMA16(a, b, c) __builtin_amdgcn_mfma_f32_16x16x32_bf16((a), (b), (c), 0, 0, 0)
;     ...
;     f32x4 o[2][8];
; #pragma unroll
;     for (int e2 = 0; e2 < 2; ++e2)
; #pragma unroll
;       for (int nt = 0; nt < 8; ++nt) o[e2][nt] = (f32x4){0.f, 0.f, 0.f, 0.f};
; #pragma unroll
;     for (int nt = 0; nt < 8; ++nt) {
; #pragma unroll
;       for (int ks = 0; ks < 4; ++ks) {
;         const bf16x8 qB = *(const LAS bf16x8*)(shm + RO_Q + (nt * 4 + ks) * 1024 + lane * 16);
;         o[0][nt] = MFMA16(rf[0][ks], qB, o[0][nt]); o[1][nt] = MFMA16(rf[1][ks], qB, o[1][nt]);
;       }
;     }
.LBB0_737:
	s_waitcnt lgkmcnt(0)
	s_barrier
	ds_read_b128 v[32:35], v131
	ds_read_b128 v[36:39], v131 offset:1024
	v_add_u32_e32 v54, 0x10000, v131
	s_waitcnt vmcnt(15) lgkmcnt(1)
	v_mfma_f32_16x16x32_bf16 v[40:43], v[12:15], v[32:35], 0
	v_and_b32_e32 v103, 64, v136
	v_xor_b32_e32 v101, 16, v136
	v_add_u32_e32 v103, 64, v103
	s_waitcnt vmcnt(7)
	v_mfma_f32_16x16x32_bf16 v[32:35], v[24:27], v[32:35], 0
	v_cmp_lt_i32_e32 vcc, v101, v103
	v_xor_b32_e32 v105, 32, v136
	s_waitcnt lgkmcnt(0)
	v_mfma_f32_16x16x32_bf16 v[40:43], v[16:19], v[36:39], v[40:43]
	v_cndmask_b32_e32 v101, v136, v101, vcc
	v_lshlrev_b32_e32 v101, 2, v101
	v_cmp_lt_i32_e32 vcc, v105, v103
	s_waitcnt vmcnt(6)
	v_mfma_f32_16x16x32_bf16 v[32:35], v[28:31], v[36:39], v[32:35]
	ds_read_b128 v[36:39], v131 offset:2048
	ds_read_b128 v[44:47], v131 offset:3072
	s_waitcnt lgkmcnt(1)
	v_mfma_f32_16x16x32_bf16 v[40:43], v[4:7], v[36:39], v[40:43]
	s_waitcnt vmcnt(3)
	v_mfma_f32_16x16x32_bf16 v[32:35], v[20:23], v[36:39], v[32:35]
	s_waitcnt lgkmcnt(0)
	v_mfma_f32_16x16x32_bf16 v[36:39], v[8:11], v[44:47], v[40:43]
	s_waitcnt vmcnt(2)
	v_mfma_f32_16x16x32_bf16 v[32:35], v[0:3], v[44:47], v[32:35]
	s_nop 1
	ds_read_b128 v[40:43], v131 offset:4096
	ds_read_b128 v[44:47], v131 offset:5120
	s_waitcnt lgkmcnt(1)
	v_mfma_f32_16x16x32_bf16 v[50:53], v[12:15], v[40:43], 0
	v_mfma_f32_16x16x32_bf16 v[40:43], v[24:27], v[40:43], 0
	s_waitcnt lgkmcnt(0)
	v_mfma_f32_16x16x32_bf16 v[50:53], v[16:19], v[44:47], v[50:53]
	v_mfma_f32_16x16x32_bf16 v[40:43], v[28:31], v[44:47], v[40:43]
	ds_read_b128 v[44:47], v131 offset:6144
	ds_read_b128 v[142:145], v131 offset:7168
	s_waitcnt lgkmcnt(1)
	v_mfma_f32_16x16x32_bf16 v[50:53], v[4:7], v[44:47], v[50:53]
	v_mfma_f32_16x16x32_bf16 v[40:43], v[20:23], v[44:47], v[40:43]
	s_waitcnt lgkmcnt(0)
	v_mfma_f32_16x16x32_bf16 v[50:53], v[8:11], v[142:145], v[50:53]
	v_mfma_f32_16x16x32_bf16 v[40:43], v[0:3], v[142:145], v[40:43]
	ds_read_b128 v[44:47], v131 offset:8192
	ds_read_b128 v[142:145], v131 offset:9216
	s_waitcnt lgkmcnt(1)
	v_mfma_f32_16x16x32_bf16 v[146:149], v[12:15], v[44:47], 0
	v_mfma_f32_16x16x32_bf16 v[44:47], v[24:27], v[44:47], 0
	s_waitcnt lgkmcnt(0)
	v_mfma_f32_16x16x32_bf16 v[146:149], v[16:19], v[142:145], v[146:149]
	v_mfma_f32_16x16x32_bf16 v[44:47], v[28:31], v[142:145], v[44:47]
	ds_read_b128 v[142:145], v131 offset:10240
	ds_read_b128 v[150:153], v131 offset:11264
	s_waitcnt lgkmcnt(1)
	v_mfma_f32_16x16x32_bf16 v[146:149], v[4:7], v[142:145], v[146:149]
	v_mfma_f32_16x16x32_bf16 v[44:47], v[20:23], v[142:145], v[44:47]
	s_waitcnt lgkmcnt(0)
	v_mfma_f32_16x16x32_bf16 v[142:145], v[8:11], v[150:153], v[146:149]
	v_mfma_f32_16x16x32_bf16 v[146:149], v[0:3], v[150:153], v[44:47]
	s_nop 4
	ds_read_b128 v[44:47], v131 offset:12288
	ds_read_b128 v[150:153], v131 offset:13312
	s_waitcnt lgkmcnt(1)
	v_mfma_f32_16x16x32_bf16 v[154:157], v[12:15], v[44:47], 0
	v_mfma_f32_16x16x32_bf16 v[44:47], v[24:27], v[44:47], 0
	s_waitcnt lgkmcnt(0)
	v_mfma_f32_16x16x32_bf16 v[154:157], v[16:19], v[150:153], v[154:157]
	v_mfma_f32_16x16x32_bf16 v[44:47], v[28:31], v[150:153], v[44:47]
	ds_read_b128 v[150:153], v131 offset:14336
	ds_read_b128 v[158:161], v131 offset:15360
	s_waitcnt lgkmcnt(1)
	v_mfma_f32_16x16x32_bf16 v[154:157], v[4:7], v[150:153], v[154:157]
	v_mfma_f32_16x16x32_bf16 v[44:47], v[20:23], v[150:153], v[44:47]
	s_waitcnt lgkmcnt(0)
	v_mfma_f32_16x16x32_bf16 v[150:153], v[8:11], v[158:161], v[154:157]
	v_mfma_f32_16x16x32_bf16 v[154:157], v[0:3], v[158:161], v[44:47]
	s_nop 4
	ds_read_b128 v[44:47], v131 offset:16384
	ds_read_b128 v[158:161], v131 offset:17408
	s_waitcnt lgkmcnt(1)
	v_mfma_f32_16x16x32_bf16 v[162:165], v[12:15], v[44:47], 0
	v_mfma_f32_16x16x32_bf16 v[44:47], v[24:27], v[44:47], 0
	s_waitcnt lgkmcnt(0)
	v_mfma_f32_16x16x32_bf16 v[162:165], v[16:19], v[158:161], v[162:165]
	v_mfma_f32_16x16x32_bf16 v[44:47], v[28:31], v[158:161], v[44:47]
	ds_read_b128 v[158:161], v131 offset:18432
	ds_read_b128 v[166:169], v131 offset:19456
	s_waitcnt lgkmcnt(1)
	v_mfma_f32_16x16x32_bf16 v[162:165], v[4:7], v[158:161], v[162:165]
	v_mfma_f32_16x16x32_bf16 v[44:47], v[20:23], v[158:161], v[44:47]
	s_waitcnt lgkmcnt(0)
	v_mfma_f32_16x16x32_bf16 v[158:161], v[8:11], v[166:169], v[162:165]
	v_mfma_f32_16x16x32_bf16 v[162:165], v[0:3], v[166:169], v[44:47]
	s_nop 4
	ds_read_b128 v[44:47], v131 offset:20480
	ds_read_b128 v[166:169], v131 offset:21504
	s_waitcnt lgkmcnt(1)
	v_mfma_f32_16x16x32_bf16 v[170:173], v[12:15], v[44:47], 0
	v_mfma_f32_16x16x32_bf16 v[44:47], v[24:27], v[44:47], 0
	s_waitcnt lgkmcnt(0)
	v_mfma_f32_16x16x32_bf16 v[170:173], v[16:19], v[166:169], v[170:173]
	v_mfma_f32_16x16x32_bf16 v[44:47], v[28:31], v[166:169], v[44:47]
	ds_read_b128 v[166:169], v131 offset:22528
	ds_read_b128 v[174:177], v131 offset:23552
	s_waitcnt lgkmcnt(1)
	v_mfma_f32_16x16x32_bf16 v[170:173], v[4:7], v[166:169], v[170:173]
	v_mfma_f32_16x16x32_bf16 v[44:47], v[20:23], v[166:169], v[44:47]
	s_waitcnt lgkmcnt(0)
	v_mfma_f32_16x16x32_bf16 v[166:169], v[8:11], v[174:177], v[170:173]
	v_mfma_f32_16x16x32_bf16 v[170:173], v[0:3], v[174:177], v[44:47]
	s_nop 4
	ds_read_b128 v[44:47], v131 offset:24576
	ds_read_b128 v[174:177], v131 offset:25600
	s_waitcnt lgkmcnt(1)
	v_mfma_f32_16x16x32_bf16 v[178:181], v[12:15], v[44:47], 0
	v_mfma_f32_16x16x32_bf16 v[44:47], v[24:27], v[44:47], 0
	s_waitcnt lgkmcnt(0)
	v_mfma_f32_16x16x32_bf16 v[178:181], v[16:19], v[174:177], v[178:181]
	v_mfma_f32_16x16x32_bf16 v[44:47], v[28:31], v[174:177], v[44:47]
	ds_read_b128 v[174:177], v131 offset:26624
	ds_read_b128 v[182:185], v131 offset:27648
	s_waitcnt lgkmcnt(1)
; #define LAS __attribute__((address_space(3)))
; #define MFMA16(a, b, c) __builtin_amdgcn_mfma_f32_16x16x32_bf16((a), (b), (c), 0, 0, 0)
;     ...
;     for (int nt = 0; nt < 8; ++nt) {
; #pragma unroll
;       for (int ks = 0; ks < 4; ++ks) {
;         const bf16x8 qB = *(const LAS bf16x8*)(shm + RO_Q + (nt * 4 + ks) * 1024 + lane * 16);
;         o[0][nt] = MFMA16(rf[0][ks], qB, o[0][nt]); o[1][nt] = MFMA16(rf[1][ks], qB, o[1][nt]);
;       }
;     }
; #pragma unroll
;     for (int nt = 0; nt < 8; ++nt) {
;       o[0][nt] = o[0][nt] * gam; o[1][nt] = o[1][nt] * gam;
; #pragma unroll
;       for (int s2 = 0; s2 < (16 * nt + 15) / 32 + 1; ++s2) {
;         const bf16x8 pB = *(const LAS bf16x8*)(shm + RO_P + (nt * 4 + s2) * 1024 + lane * 16);
;         o[0][nt] = MFMA16(vf[0][s2], pB, o[0][nt]); o[1][nt] = MFMA16(vf[1][s2], pB, o[1][nt]);
;       }
;     }
	v_mfma_f32_16x16x32_bf16 v[178:181], v[4:7], v[174:177], v[178:181]
	v_mfma_f32_16x16x32_bf16 v[44:47], v[20:23], v[174:177], v[44:47]
	s_waitcnt lgkmcnt(0)
	v_mfma_f32_16x16x32_bf16 v[174:177], v[8:11], v[182:185], v[178:181]
	v_mfma_f32_16x16x32_bf16 v[178:181], v[0:3], v[182:185], v[44:47]
	s_nop 4
	ds_read_b128 v[44:47], v131 offset:28672
	ds_read_b128 v[182:185], v131 offset:29696
	s_waitcnt lgkmcnt(1)
	v_mfma_f32_16x16x32_bf16 v[12:15], v[12:15], v[44:47], 0
	v_mfma_f32_16x16x32_bf16 v[24:27], v[24:27], v[44:47], 0
	s_waitcnt lgkmcnt(0)
	v_mfma_f32_16x16x32_bf16 v[12:15], v[16:19], v[182:185], v[12:15]
	v_mfma_f32_16x16x32_bf16 v[16:19], v[28:31], v[182:185], v[24:27]
	s_nop 4
	ds_read_b128 v[24:27], v131 offset:30720
	ds_read_b128 v[28:31], v131 offset:31744
	s_waitcnt lgkmcnt(1)
	v_mfma_f32_16x16x32_bf16 v[4:7], v[4:7], v[24:27], v[12:15]
	v_mfma_f32_16x16x32_bf16 v[12:15], v[20:23], v[24:27], v[16:19]
	s_waitcnt lgkmcnt(0)
	v_mfma_f32_16x16x32_bf16 v[182:185], v[8:11], v[28:31], v[4:7]
	ds_read_b128 v[8:11], v54 offset:4096
	ds_read_b128 v[16:19], v54 offset:9216
	s_nop 2
	ds_read_b128 v[4:7], v54
	v_mfma_f32_16x16x32_bf16 v[186:189], v[0:3], v[28:31], v[12:15]
	v_mul_f32_e64 v2, v48, v38
	v_mul_f32_e64 v3, v48, v39
	v_pk_mul_f32 v[0:1], v[48:49], v[36:37] op_sel_hi:[0,1]
	v_pk_mul_f32 v[30:31], v[48:49], v[156:157] op_sel_hi:[0,1]
	ds_read_b128 v[12:15], v54 offset:8192
	s_waitcnt lgkmcnt(1)
	v_mfma_f32_16x16x32_bf16 v[44:47], v[76:79], v[4:7], v[0:3]
	v_mul_f32_e64 v28, v48, v154
	v_mul_f32_e64 v29, v48, v155
	s_nop 0
	v_pk_mul_f32 v[2:3], v[48:49], v[34:35] op_sel_hi:[0,1]
	v_pk_mul_f32 v[0:1], v[48:49], v[32:33] op_sel_hi:[0,1]
	ds_read_b128 v[32:35], v54 offset:17408
	s_nop 0
	v_mfma_f32_16x16x32_bf16 v[36:39], v[84:87], v[4:7], v[0:3]
	s_nop 2
	v_mul_f32_e64 v2, v48, v52
	v_mul_f32_e64 v3, v48, v53
	v_pk_mul_f32 v[0:1], v[48:49], v[50:51] op_sel_hi:[0,1]
	s_nop 1
	v_mfma_f32_16x16x32_bf16 v[4:7], v[76:79], v[8:11], v[0:3]
	s_nop 2
	v_mul_f32_e64 v2, v48, v42
	v_mul_f32_e64 v3, v48, v43
	v_pk_mul_f32 v[0:1], v[48:49], v[40:41] op_sel_hi:[0,1]
	v_pk_mul_f32 v[42:43], v[48:49], v[164:165] op_sel_hi:[0,1]
	v_pk_mul_f32 v[40:41], v[48:49], v[162:163] op_sel_hi:[0,1]
	v_mfma_f32_16x16x32_bf16 v[24:27], v[84:87], v[8:11], v[0:3]
	v_mul_f32_e64 v10, v48, v148
	v_mul_f32_e64 v11, v48, v149
	v_pk_mul_f32 v[8:9], v[48:49], v[146:147] op_sel_hi:[0,1]
	v_pk_mul_f32 v[164:165], v[48:49], v[184:185] op_sel_hi:[0,1]
	v_pk_mul_f32 v[2:3], v[48:49], v[144:145] op_sel_hi:[0,1]
	v_pk_mul_f32 v[0:1], v[48:49], v[142:143] op_sel_hi:[0,1]
	v_pk_mul_f32 v[162:163], v[48:49], v[182:183] op_sel_hi:[0,1]
	s_waitcnt lgkmcnt(1)
	v_mfma_f32_16x16x32_bf16 v[0:3], v[76:79], v[12:15], v[0:3]
	v_mfma_f32_16x16x32_bf16 v[12:15], v[84:87], v[12:15], v[8:11]
	v_mfma_f32_16x16x32_bf16 v[8:11], v[68:71], v[16:19], v[0:3]
	s_nop 5
	ds_read_b128 v[0:3], v54 offset:12288
	v_mfma_f32_16x16x32_bf16 v[20:23], v[80:83], v[16:19], v[12:15]
	ds_read_b128 v[16:19], v54 offset:13312
	s_nop 1
	v_pk_mul_f32 v[14:15], v[48:49], v[152:153] op_sel_hi:[0,1]
	v_pk_mul_f32 v[12:13], v[48:49], v[150:151] op_sel_hi:[0,1]
	s_waitcnt lgkmcnt(1)
	v_mfma_f32_16x16x32_bf16 v[28:31], v[84:87], v[0:3], v[28:31]
	v_mfma_f32_16x16x32_bf16 v[12:15], v[76:79], v[0:3], v[12:15]
	s_waitcnt lgkmcnt(0)
	v_mfma_f32_16x16x32_bf16 v[0:3], v[68:71], v[16:19], v[12:15]
	v_mfma_f32_16x16x32_bf16 v[16:19], v[80:83], v[16:19], v[28:31]
	s_nop 4
	ds_read_b128 v[12:15], v54 offset:16384
	v_pk_mul_f32 v[30:31], v[48:49], v[160:161] op_sel_hi:[0,1]
	v_pk_mul_f32 v[28:29], v[48:49], v[158:159] op_sel_hi:[0,1]
	s_waitcnt lgkmcnt(0)
	s_nop 0
	v_mfma_f32_16x16x32_bf16 v[28:31], v[76:79], v[12:15], v[28:31]
	v_mfma_f32_16x16x32_bf16 v[12:15], v[84:87], v[12:15], v[40:43]
	v_mfma_f32_16x16x32_bf16 v[28:31], v[68:71], v[32:35], v[28:31]
	v_mfma_f32_16x16x32_bf16 v[12:15], v[80:83], v[32:35], v[12:15]
	ds_read_b128 v[32:35], v54 offset:18432
	ds_read_b128 v[50:53], v54 offset:20480
	s_waitcnt lgkmcnt(1)
	v_mfma_f32_16x16x32_bf16 v[40:43], v[60:63], v[32:35], v[28:31]
	s_waitcnt vmcnt(1)
	v_mfma_f32_16x16x32_bf16 v[28:31], v[72:75], v[32:35], v[12:15]
	v_mul_f32_e64 v34, v48, v172
	v_mul_f32_e64 v35, v48, v173
	v_pk_mul_f32 v[32:33], v[48:49], v[170:171] op_sel_hi:[0,1]
	v_pk_mul_f32 v[14:15], v[48:49], v[168:169] op_sel_hi:[0,1]
	v_pk_mul_f32 v[12:13], v[48:49], v[166:167] op_sel_hi:[0,1]
	s_waitcnt lgkmcnt(0)
	v_mfma_f32_16x16x32_bf16 v[32:35], v[84:87], v[50:53], v[32:35]
	v_mfma_f32_16x16x32_bf16 v[12:15], v[76:79], v[50:53], v[12:15]
	ds_read_b128 v[50:53], v54 offset:21504
	ds_read_b128 v[142:145], v54 offset:22528
	ds_read_b128 v[146:149], v54 offset:24576
	ds_read_b128 v[150:153], v54 offset:25600
	s_waitcnt lgkmcnt(3)
	v_mfma_f32_16x16x32_bf16 v[12:15], v[68:71], v[50:53], v[12:15]
	ds_read_b128 v[154:157], v54 offset:26624
	ds_read_b128 v[158:161], v54 offset:27648
	v_mfma_f32_16x16x32_bf16 v[32:35], v[80:83], v[50:53], v[32:35]
	v_mul_f32_e64 v52, v48, v176
	v_mul_f32_e64 v53, v48, v177
	v_pk_mul_f32 v[50:51], v[48:49], v[174:175] op_sel_hi:[0,1]
	s_waitcnt lgkmcnt(4)
	v_mfma_f32_16x16x32_bf16 v[12:15], v[60:63], v[142:145], v[12:15]
	v_mfma_f32_16x16x32_bf16 v[32:35], v[72:75], v[142:145], v[32:35]
	v_mul_f32_e64 v144, v48, v180
	v_mul_f32_e64 v145, v48, v181
	v_pk_mul_f32 v[142:143], v[48:49], v[178:179] op_sel_hi:[0,1]
	ds_read_b128 v[166:169], v54 offset:28672
	ds_read_b128 v[170:173], v54 offset:29696
	ds_read_b128 v[174:177], v54 offset:30720
	ds_read_b128 v[178:181], v54 offset:31744
	s_waitcnt lgkmcnt(7)
; #define LAS __attribute__((address_space(3)))
; #define MFMA16(a, b, c) __builtin_amdgcn_mfma_f32_16x16x32_bf16((a), (b), (c), 0, 0, 0)
;     ...
; #pragma unroll
;     for (int nt = 0; nt < 8; ++nt) {
;       o[0][nt] = o[0][nt] * gam; o[1][nt] = o[1][nt] * gam;
; #pragma unroll
;       for (int s2 = 0; s2 < (16 * nt + 15) / 32 + 1; ++s2) {
;         const bf16x8 pB = *(const LAS bf16x8*)(shm + RO_P + (nt * 4 + s2) * 1024 + lane * 16);
;         o[0][nt] = MFMA16(vf[0][s2], pB, o[0][nt]); o[1][nt] = MFMA16(vf[1][s2], pB, o[1][nt]);
;       }
;     }
;     {
;       LAS f32x2* part = (LAS f32x2*)(shm + RO_PART);
; #pragma unroll
;       for (int nt = 0; nt < 8; ++nt) {
;         float s1 = 0.f, s2q = 0.f;
; #pragma unroll
;         for (int e2 = 0; e2 < 2; ++e2)
; #pragma unroll
;           for (int i = 0; i < 4; ++i) { const float v = o[e2][nt][i]; s1 += v; s2q += v * v; }
;         s1 += __shfl_xor(s1, 16); s1 += __shfl_xor(s1, 32); s2q += __shfl_xor(s2q, 16); s2q += __shfl_xor(s2q, 32);
;         if (fq == 0) part[wid * 128 + nt * 16 + fr] = (f32x2){s1, s2q};
;       }
;     }
	v_mfma_f32_16x16x32_bf16 v[50:53], v[76:79], v[146:149], v[50:53]
	v_mfma_f32_16x16x32_bf16 v[142:145], v[84:87], v[146:149], v[142:145]
	v_mul_f32_e64 v148, v48, v188
	v_mul_f32_e64 v149, v48, v189
	v_pk_mul_f32 v[146:147], v[48:49], v[186:187] op_sel_hi:[0,1]
	s_waitcnt lgkmcnt(6)
	v_mfma_f32_16x16x32_bf16 v[48:51], v[68:71], v[150:153], v[50:53]
	v_mfma_f32_16x16x32_bf16 v[52:55], v[80:83], v[150:153], v[142:145]
	v_mul_f32_e64 v152, v44, v44
	v_mul_f32_e64 v153, v45, v45
	v_pk_mul_f32 v[150:151], v[46:47], v[46:47]
	v_fmac_f32_e32 v153, v44, v44
	s_waitcnt lgkmcnt(5)
	v_mfma_f32_16x16x32_bf16 v[48:51], v[60:63], v[154:157], v[48:51]
	v_add_f32_e32 v109, v150, v153
	v_mfma_f32_16x16x32_bf16 v[142:145], v[72:75], v[154:157], v[52:55]
	s_nop 2
	v_add_f32_e32 v52, 0, v44
	s_waitcnt lgkmcnt(3)
	v_mfma_f32_16x16x32_bf16 v[76:79], v[76:79], v[166:169], v[162:165]
	v_add_f32_e32 v52, v45, v52
	v_add_f32_e32 v107, v46, v52
	v_add_f32_e32 v107, v47, v107
	v_mfma_f32_16x16x32_bf16 v[52:55], v[56:59], v[158:161], v[48:51]
	v_add_f32_e32 v107, v36, v107
	v_add_f32_e32 v107, v37, v107
	s_waitcnt vmcnt(0)
	v_mfma_f32_16x16x32_bf16 v[48:51], v[64:67], v[158:161], v[142:145]
	s_nop 2
	v_mov_b32_e32 v142, v36
	v_mov_b32_e32 v143, v47
	v_mfma_f32_16x16x32_bf16 v[84:87], v[84:87], v[166:169], v[146:149]
	v_mul_f32_e64 v142, v142, v142
	v_mul_f32_e64 v143, v143, v143
	v_pk_mul_f32 v[144:145], v[38:39], v[38:39]
	v_add_f32_e32 v109, v143, v109
	s_waitcnt lgkmcnt(2)
	v_mfma_f32_16x16x32_bf16 v[68:71], v[68:71], v[170:173], v[76:79]
	v_add_f32_e32 v109, v142, v109
	v_pk_mul_f32 v[146:147], v[36:37], v[36:37]
	v_add_f32_e32 v142, v38, v107
	v_mfma_f32_16x16x32_bf16 v[76:79], v[80:83], v[170:173], v[84:87]
	v_add_f32_e32 v80, v147, v109
	v_add_f32_e32 v81, v144, v80
	v_mul_f32_e32 v143, v39, v39
	v_mov_b32_e32 v80, v39
	s_waitcnt lgkmcnt(1)
	v_mfma_f32_16x16x32_bf16 v[60:63], v[60:63], v[174:177], v[68:71]
	s_nop 2
	v_add_f32_e64 v68, v80, v142
	v_add_f32_e64 v69, v81, v143
	v_mov_b32_e32 v70, v68
	v_mov_b32_e32 v71, v69
	s_nop 1
	v_permlane16_swap_b32_e32 v68, v70
	v_permlane16_swap_b32_e32 v69, v71
	v_mfma_f32_16x16x32_bf16 v[74:77], v[72:75], v[174:177], v[76:79]
	v_cndmask_b32_e32 v72, v136, v105, vcc
	v_lshlrev_b32_e32 v72, 2, v72
	s_waitcnt lgkmcnt(0)
	v_pk_add_f32 v[68:69], v[68:69], v[70:71]
	v_mov_b32_e32 v70, v68
	v_mov_b32_e32 v71, v69
	s_nop 1
	v_permlane32_swap_b32_e32 v68, v70
	v_permlane32_swap_b32_e32 v69, v71
	v_mfma_f32_16x16x32_bf16 v[60:63], v[56:59], v[178:181], v[60:63]
	v_mfma_f32_16x16x32_bf16 v[56:59], v[64:67], v[178:181], v[74:77]
	s_and_saveexec_b64 s[0:1], s[6:7]
	s_cbranch_execz .LBB0_739
	s_waitcnt lgkmcnt(0)
	v_pk_add_f32 v[64:65], v[68:69], v[70:71]
	v_add_u32_e32 v66, s30, v120
	ds_write_b64 v66, v[64:65]
.LBB0_739:
	s_or_b64 exec, exec, s[0:1]
	v_add_f32_e32 v64, 0, v4
	v_add_f32_e32 v64, v5, v64
	v_pk_mul_f32 v[66:67], v[4:5], v[4:5]
	v_add_f32_e32 v68, v6, v64
	v_pk_mul_f32 v[64:65], v[6:7], v[6:7]
	v_fmac_f32_e32 v67, v4, v4
	v_add_f32_e32 v66, v64, v67
	v_add_f32_e32 v64, v7, v68
	v_add_f32_e32 v67, v24, v64
	v_mov_b32_e32 v64, v24
	v_mov_b32_e32 v65, v7
	v_pk_mul_f32 v[64:65], v[64:65], v[64:65]
	v_pk_mul_f32 v[68:69], v[24:25], v[24:25]
	v_add_f32_e32 v65, v65, v66
	v_add_f32_e32 v65, v64, v65
	v_add_f32_e32 v64, v25, v67
	v_pk_mul_f32 v[66:67], v[26:27], v[26:27]
	v_add_f32_e32 v65, v69, v65
	v_add_f32_e32 v64, v26, v64
	v_add_f32_e32 v67, v66, v65
	v_mul_f32_e32 v65, v27, v27
	v_mov_b32_e32 v66, v27
	v_pk_add_f32 v[64:65], v[66:67], v[64:65]
	v_mov_b32_e32 v66, v64
	v_mov_b32_e32 v67, v65
	s_nop 1
	v_permlane16_swap_b32_e32 v64, v66
	v_permlane16_swap_b32_e32 v65, v67
	s_waitcnt lgkmcnt(0)
	v_pk_add_f32 v[64:65], v[64:65], v[66:67]
	v_mov_b32_e32 v66, v64
	v_mov_b32_e32 v67, v65
	s_nop 1
	v_permlane32_swap_b32_e32 v64, v66
	v_permlane32_swap_b32_e32 v65, v67
	s_and_saveexec_b64 s[0:1], s[6:7]
	s_cbranch_execz .LBB0_741
	s_waitcnt lgkmcnt(0)
	v_pk_add_f32 v[64:65], v[64:65], v[66:67]
	v_add_u32_e32 v66, s30, v120
	ds_write_b64 v66, v[64:65] offset:128
.LBB0_741:
	s_or_b64 exec, exec, s[0:1]
	v_add_f32_e32 v64, 0, v8
	v_add_f32_e32 v64, v9, v64
	s_waitcnt lgkmcnt(0)
	v_pk_mul_f32 v[66:67], v[8:9], v[8:9]
	v_add_f32_e32 v68, v10, v64
	v_pk_mul_f32 v[64:65], v[10:11], v[10:11]
	v_fmac_f32_e32 v67, v8, v8
	v_add_f32_e32 v66, v64, v67
	v_add_f32_e32 v64, v11, v68
	v_add_f32_e32 v67, v20, v64
	v_mov_b32_e32 v64, v20
	v_mov_b32_e32 v65, v11
	v_pk_mul_f32 v[64:65], v[64:65], v[64:65]
	v_pk_mul_f32 v[68:69], v[20:21], v[20:21]
	v_add_f32_e32 v65, v65, v66
	v_add_f32_e32 v65, v64, v65
	v_add_f32_e32 v64, v21, v67
	v_pk_mul_f32 v[66:67], v[22:23], v[22:23]
	v_add_f32_e32 v65, v69, v65
	v_add_f32_e32 v64, v22, v64
	v_add_f32_e32 v67, v66, v65
	v_mul_f32_e32 v65, v23, v23
	v_mov_b32_e32 v66, v23
	v_pk_add_f32 v[64:65], v[66:67], v[64:65]
	v_mov_b32_e32 v66, v64
	v_mov_b32_e32 v67, v65
	s_nop 1
	v_permlane16_swap_b32_e32 v64, v66
	v_permlane16_swap_b32_e32 v65, v67
	s_waitcnt lgkmcnt(0)
	v_pk_add_f32 v[64:65], v[64:65], v[66:67]
	v_mov_b32_e32 v66, v64
	v_mov_b32_e32 v67, v65
	s_nop 1
	v_permlane32_swap_b32_e32 v64, v66
	v_permlane32_swap_b32_e32 v65, v67
	s_and_saveexec_b64 s[0:1], s[6:7]
	s_cbranch_execz .LBB0_743
	s_waitcnt lgkmcnt(0)
	v_pk_add_f32 v[64:65], v[64:65], v[66:67]
	v_add_u32_e32 v66, s30, v120
	ds_write_b64 v66, v[64:65] offset:256
; #define LAS __attribute__((address_space(3)))
;     ...
;     {
;       LAS f32x2* part = (LAS f32x2*)(shm + RO_PART);
; #pragma unroll
;       for (int nt = 0; nt < 8; ++nt) {
;         float s1 = 0.f, s2q = 0.f;
; #pragma unroll
;         for (int e2 = 0; e2 < 2; ++e2)
; #pragma unroll
;           for (int i = 0; i < 4; ++i) { const float v = o[e2][nt][i]; s1 += v; s2q += v * v; }
;         s1 += __shfl_xor(s1, 16); s1 += __shfl_xor(s1, 32); s2q += __shfl_xor(s2q, 16); s2q += __shfl_xor(s2q, 32);
;         if (fq == 0) part[wid * 128 + nt * 16 + fr] = (f32x2){s1, s2q};
;       }
;     }
.LBB0_743:
	s_or_b64 exec, exec, s[0:1]
	v_add_f32_e32 v64, 0, v0
	v_add_f32_e32 v64, v1, v64
	s_waitcnt lgkmcnt(0)
	v_pk_mul_f32 v[66:67], v[0:1], v[0:1]
	v_add_f32_e32 v68, v2, v64
	v_pk_mul_f32 v[64:65], v[2:3], v[2:3]
	v_fmac_f32_e32 v67, v0, v0
	v_add_f32_e32 v66, v64, v67
	v_add_f32_e32 v64, v3, v68
	v_add_f32_e32 v67, v16, v64
	v_mov_b32_e32 v64, v16
	v_mov_b32_e32 v65, v3
	v_pk_mul_f32 v[64:65], v[64:65], v[64:65]
	v_pk_mul_f32 v[68:69], v[16:17], v[16:17]
	v_add_f32_e32 v65, v65, v66
	v_add_f32_e32 v65, v64, v65
	v_add_f32_e32 v64, v17, v67
	v_pk_mul_f32 v[66:67], v[18:19], v[18:19]
	v_add_f32_e32 v65, v69, v65
	v_add_f32_e32 v64, v18, v64
	v_add_f32_e32 v67, v66, v65
	v_mul_f32_e32 v65, v19, v19
	v_mov_b32_e32 v66, v19
	v_pk_add_f32 v[64:65], v[66:67], v[64:65]
	v_mov_b32_e32 v66, v64
	v_mov_b32_e32 v67, v65
	s_nop 1
	v_permlane16_swap_b32_e32 v64, v66
	v_permlane16_swap_b32_e32 v65, v67
	s_waitcnt lgkmcnt(0)
	v_pk_add_f32 v[64:65], v[64:65], v[66:67]
	v_mov_b32_e32 v66, v64
	v_mov_b32_e32 v67, v65
	s_nop 1
	v_permlane32_swap_b32_e32 v64, v66
	v_permlane32_swap_b32_e32 v65, v67
	s_and_saveexec_b64 s[0:1], s[6:7]
	s_cbranch_execz .LBB0_745
	s_waitcnt lgkmcnt(0)
	v_pk_add_f32 v[64:65], v[64:65], v[66:67]
	v_add_u32_e32 v66, s30, v120
	ds_write_b64 v66, v[64:65] offset:384
.LBB0_745:
	s_or_b64 exec, exec, s[0:1]
	v_add_f32_e32 v64, 0, v40
	v_add_f32_e32 v64, v41, v64
	s_waitcnt lgkmcnt(0)
	v_pk_mul_f32 v[66:67], v[40:41], v[40:41]
	v_add_f32_e32 v68, v42, v64
	v_pk_mul_f32 v[64:65], v[42:43], v[42:43]
	v_fmac_f32_e32 v67, v40, v40
	v_add_f32_e32 v66, v64, v67
	v_add_f32_e32 v64, v43, v68
	v_add_f32_e32 v67, v28, v64
	v_mov_b32_e32 v64, v28
	v_mov_b32_e32 v65, v43
	v_pk_mul_f32 v[64:65], v[64:65], v[64:65]
	v_pk_mul_f32 v[68:69], v[28:29], v[28:29]
	v_add_f32_e32 v65, v65, v66
	v_add_f32_e32 v65, v64, v65
	v_add_f32_e32 v64, v29, v67
	v_pk_mul_f32 v[66:67], v[30:31], v[30:31]
	v_add_f32_e32 v65, v69, v65
	v_add_f32_e32 v64, v30, v64
	v_add_f32_e32 v67, v66, v65
	v_mul_f32_e32 v65, v31, v31
	v_mov_b32_e32 v66, v31
	v_pk_add_f32 v[64:65], v[66:67], v[64:65]
	v_mov_b32_e32 v66, v64
	v_mov_b32_e32 v67, v65
	s_nop 1
	v_permlane16_swap_b32_e32 v64, v66
	v_permlane16_swap_b32_e32 v65, v67
	s_waitcnt lgkmcnt(0)
	v_pk_add_f32 v[64:65], v[64:65], v[66:67]
	v_mov_b32_e32 v66, v64
	v_mov_b32_e32 v67, v65
	s_nop 1
	v_permlane32_swap_b32_e32 v64, v66
	v_permlane32_swap_b32_e32 v65, v67
	s_and_saveexec_b64 s[0:1], s[6:7]
	s_cbranch_execz .LBB0_747
	s_waitcnt lgkmcnt(0)
	v_pk_add_f32 v[64:65], v[64:65], v[66:67]
	v_add_u32_e32 v66, s30, v120
	ds_write_b64 v66, v[64:65] offset:512
.LBB0_747:
	s_or_b64 exec, exec, s[0:1]
	v_add_f32_e32 v64, 0, v12
	v_add_f32_e32 v64, v13, v64
	s_waitcnt lgkmcnt(0)
	v_pk_mul_f32 v[66:67], v[12:13], v[12:13]
	v_add_f32_e32 v68, v14, v64
	v_pk_mul_f32 v[64:65], v[14:15], v[14:15]
	v_fmac_f32_e32 v67, v12, v12
	v_add_f32_e32 v66, v64, v67
	v_add_f32_e32 v64, v15, v68
	v_add_f32_e32 v67, v32, v64
	v_mov_b32_e32 v64, v32
	v_mov_b32_e32 v65, v15
	v_pk_mul_f32 v[64:65], v[64:65], v[64:65]
	v_pk_mul_f32 v[68:69], v[32:33], v[32:33]
	v_add_f32_e32 v65, v65, v66
	v_add_f32_e32 v65, v64, v65
	v_add_f32_e32 v64, v33, v67
	v_pk_mul_f32 v[66:67], v[34:35], v[34:35]
	v_add_f32_e32 v65, v69, v65
	v_add_f32_e32 v64, v34, v64
	v_add_f32_e32 v67, v66, v65
	v_mul_f32_e32 v65, v35, v35
	v_mov_b32_e32 v66, v35
	v_pk_add_f32 v[64:65], v[66:67], v[64:65]
	v_mov_b32_e32 v66, v64
	v_mov_b32_e32 v67, v65
	s_nop 1
	v_permlane16_swap_b32_e32 v64, v66
	v_permlane16_swap_b32_e32 v65, v67
	s_waitcnt lgkmcnt(0)
	v_pk_add_f32 v[64:65], v[64:65], v[66:67]
	v_mov_b32_e32 v66, v64
	v_mov_b32_e32 v67, v65
	s_nop 1
	v_permlane32_swap_b32_e32 v64, v66
	v_permlane32_swap_b32_e32 v65, v67
	s_and_saveexec_b64 s[0:1], s[6:7]
	s_cbranch_execz .LBB0_749
	s_waitcnt lgkmcnt(0)
	v_pk_add_f32 v[64:65], v[64:65], v[66:67]
	v_add_u32_e32 v66, s30, v120
	ds_write_b64 v66, v[64:65] offset:640
.LBB0_749:
	s_or_b64 exec, exec, s[0:1]
	v_add_f32_e32 v64, 0, v52
	v_add_f32_e32 v64, v53, v64
	s_waitcnt lgkmcnt(0)
	v_pk_mul_f32 v[66:67], v[52:53], v[52:53]
	v_add_f32_e32 v68, v54, v64
	v_pk_mul_f32 v[64:65], v[54:55], v[54:55]
	v_fmac_f32_e32 v67, v52, v52
	v_add_f32_e32 v66, v64, v67
	v_add_f32_e32 v64, v55, v68
	v_add_f32_e32 v67, v48, v64
	v_mov_b32_e32 v64, v48
	v_mov_b32_e32 v65, v55
	v_pk_mul_f32 v[64:65], v[64:65], v[64:65]
	v_pk_mul_f32 v[68:69], v[48:49], v[48:49]
	v_add_f32_e32 v65, v65, v66
	v_add_f32_e32 v65, v64, v65
	v_add_f32_e32 v64, v49, v67
	v_pk_mul_f32 v[66:67], v[50:51], v[50:51]
	v_add_f32_e32 v65, v69, v65
	v_add_f32_e32 v64, v50, v64
	v_add_f32_e32 v67, v66, v65
	v_mul_f32_e32 v65, v51, v51
	v_mov_b32_e32 v66, v51
	v_pk_add_f32 v[64:65], v[66:67], v[64:65]
	v_mov_b32_e32 v66, v64
	v_mov_b32_e32 v67, v65
	s_nop 1
	v_permlane16_swap_b32_e32 v64, v66
	v_permlane16_swap_b32_e32 v65, v67
	s_waitcnt lgkmcnt(0)
	v_pk_add_f32 v[64:65], v[64:65], v[66:67]
	v_mov_b32_e32 v66, v64
	v_mov_b32_e32 v67, v65
	s_nop 1
	v_permlane32_swap_b32_e32 v64, v66
	v_permlane32_swap_b32_e32 v65, v67
	s_and_saveexec_b64 s[0:1], s[6:7]
	s_cbranch_execz .LBB0_751
	s_waitcnt lgkmcnt(0)
	v_pk_add_f32 v[64:65], v[64:65], v[66:67]
	v_add_u32_e32 v66, s30, v120
	ds_write_b64 v66, v[64:65] offset:768
.LBB0_751:
	s_or_b64 exec, exec, s[0:1]
	v_add_f32_e32 v64, 0, v60
	v_add_f32_e32 v64, v61, v64
	s_waitcnt lgkmcnt(0)
	v_pk_mul_f32 v[66:67], v[60:61], v[60:61]
	v_add_f32_e32 v68, v62, v64
	v_pk_mul_f32 v[64:65], v[62:63], v[62:63]
	v_fmac_f32_e32 v67, v60, v60
	v_add_f32_e32 v66, v64, v67
	v_add_f32_e32 v64, v63, v68
	v_add_f32_e32 v67, v56, v64
	v_mov_b32_e32 v64, v56
	v_mov_b32_e32 v65, v63
	v_pk_mul_f32 v[64:65], v[64:65], v[64:65]
	v_pk_mul_f32 v[68:69], v[56:57], v[56:57]
	v_add_f32_e32 v65, v65, v66
	v_add_f32_e32 v65, v64, v65
	v_add_f32_e32 v64, v57, v67
	v_pk_mul_f32 v[66:67], v[58:59], v[58:59]
	v_add_f32_e32 v65, v69, v65
	v_add_f32_e32 v64, v58, v64
	v_add_f32_e32 v67, v66, v65
	v_mul_f32_e32 v65, v59, v59
	v_mov_b32_e32 v66, v59
	v_pk_add_f32 v[64:65], v[66:67], v[64:65]
	v_mov_b32_e32 v66, v64
	v_mov_b32_e32 v67, v65
	s_nop 1
	v_permlane16_swap_b32_e32 v64, v66
	v_permlane16_swap_b32_e32 v65, v67
	s_waitcnt lgkmcnt(0)
	v_pk_add_f32 v[64:65], v[64:65], v[66:67]
	v_mov_b32_e32 v66, v64
	v_mov_b32_e32 v67, v65
	s_nop 1
	v_permlane32_swap_b32_e32 v64, v66
	v_permlane32_swap_b32_e32 v65, v67
	s_and_saveexec_b64 s[0:1], s[6:7]
	s_cbranch_execz .LBB0_753
	s_waitcnt lgkmcnt(0)
	v_pk_add_f32 v[64:65], v[64:65], v[66:67]
	v_add_u32_e32 v66, s30, v120
	ds_write_b64 v66, v[64:65] offset:896
